# L6 residual epilogue pipelined 3 row-blocks deep (third rotating register set), counted vmcnt 24
# speedup vs baseline: 1.1731x; 1.0031x over previous
.LBB0_1137:
	s_waitcnt vmcnt(9)
	ds_write_b128 v204, v[96:99]
	s_waitcnt vmcnt(8)
	ds_write_b128 v204, v[100:103] offset:4608
	s_waitcnt vmcnt(7)
	ds_write_b128 v204, v[104:107] offset:9216
	s_waitcnt vmcnt(6)
	ds_write_b128 v204, v[108:111] offset:13824
	s_waitcnt vmcnt(5)
	ds_write_b128 v204, v[112:115] offset:18432
	s_waitcnt vmcnt(4)
	ds_write_b128 v204, v[116:119] offset:23040
	s_waitcnt vmcnt(3)
	ds_write_b128 v204, v[120:123] offset:27648
	s_waitcnt vmcnt(2)
	ds_write_b128 v204, v[124:127] offset:32256
	s_waitcnt vmcnt(1)
	ds_write_b128 v204, v[128:131] offset:36864
	s_waitcnt vmcnt(0)
	ds_write_b128 v204, v[132:135] offset:41472
	s_waitcnt lgkmcnt(0)
	s_barrier
	ds_read_b128 v[96:99], v206
	ds_read_b128 v[100:103], v205 offset:27648
	ds_read_b128 v[120:123], v205 offset:27712
	ds_read_b128 v[104:107], v206 offset:64
	ds_read_b128 v[108:111], v205 offset:29952
	ds_read_b128 v[132:135], v205 offset:30016
	ds_read_b128 v[112:115], v205 offset:32256
	ds_read_b128 v[208:211], v205 offset:32320
	ds_read_b128 v[116:119], v205 offset:34560
	ds_read_b128 v[136:139], v205 offset:34624
	s_waitcnt lgkmcnt(8)
	v_mfma_f32_16x16x32_bf16 v[80:83], v[96:99], v[100:103], v[80:83]
	s_mov_b32 s6, 0xf600000
	s_waitcnt lgkmcnt(5)
	v_mfma_f32_16x16x32_bf16 v[72:75], v[96:99], v[108:111], v[72:75]
	s_waitcnt lgkmcnt(3)
	v_mfma_f32_16x16x32_bf16 v[60:63], v[96:99], v[112:115], v[60:63]
	s_waitcnt lgkmcnt(1)
	v_mfma_f32_16x16x32_bf16 v[56:59], v[96:99], v[116:119], v[56:59]
	ds_read_b128 v[96:99], v206 offset:2304
	ds_read_b128 v[124:127], v206 offset:2368
	s_waitcnt lgkmcnt(1)
	v_mfma_f32_16x16x32_bf16 v[52:55], v[96:99], v[100:103], v[52:55]
	v_mfma_f32_16x16x32_bf16 v[48:51], v[96:99], v[108:111], v[48:51]
	v_mfma_f32_16x16x32_bf16 v[36:39], v[96:99], v[112:115], v[36:39]
	v_mfma_f32_16x16x32_bf16 v[24:27], v[96:99], v[116:119], v[24:27]
	ds_read_b128 v[96:99], v206 offset:4608
	ds_read_b128 v[128:131], v206 offset:4672
	s_waitcnt lgkmcnt(1)
	v_mfma_f32_16x16x32_bf16 v[8:11], v[96:99], v[100:103], v[8:11]
	v_mfma_f32_16x16x32_bf16 v[0:3], v[96:99], v[108:111], v[0:3]
	v_mfma_f32_16x16x32_bf16 v[12:15], v[96:99], v[112:115], v[12:15]
	v_mfma_f32_16x16x32_bf16 v[20:23], v[96:99], v[116:119], v[20:23]
	ds_read_b128 v[96:99], v206 offset:6912
	ds_read_b128 v[212:215], v206 offset:6976
	s_waitcnt lgkmcnt(1)
	v_mfma_f32_16x16x32_bf16 v[4:7], v[96:99], v[100:103], v[4:7]
	v_mfma_f32_16x16x32_bf16 v[16:19], v[96:99], v[108:111], v[16:19]
	v_mfma_f32_16x16x32_bf16 v[32:35], v[96:99], v[112:115], v[32:35]
	v_mfma_f32_16x16x32_bf16 v[44:47], v[96:99], v[116:119], v[44:47]
	ds_read_b128 v[96:99], v206 offset:9216
	ds_read_b128 v[216:219], v206 offset:9280
	s_waitcnt lgkmcnt(1)
	v_mfma_f32_16x16x32_bf16 v[28:31], v[96:99], v[100:103], v[28:31]
	v_mfma_f32_16x16x32_bf16 v[40:43], v[96:99], v[108:111], v[40:43]
	v_mfma_f32_16x16x32_bf16 v[88:91], v[96:99], v[112:115], v[88:91]
	v_mfma_f32_16x16x32_bf16 v[84:87], v[96:99], v[116:119], v[84:87]
	ds_read_b128 v[96:99], v206 offset:11520
	ds_read_b128 v[140:143], v206 offset:11584
	s_waitcnt lgkmcnt(1)
	v_mfma_f32_16x16x32_bf16 v[76:79], v[96:99], v[100:103], v[76:79]
	v_mfma_f32_16x16x32_bf16 v[68:71], v[96:99], v[108:111], v[68:71]
	v_mfma_f32_16x16x32_bf16 v[64:67], v[96:99], v[112:115], v[64:67]
	v_mfma_f32_16x16x32_bf16 v[92:95], v[96:99], v[116:119], v[92:95]
	v_lshl_add_u64 v[96:97], v[162:163], 0, s[2:3]
	v_add_co_u32_e32 v100, vcc, s6, v96
	s_mov_b32 s6, 0xf610000
	s_nop 0
	v_addc_co_u32_e32 v101, vcc, 0, v97, vcc
	v_add_co_u32_e32 v102, vcc, s6, v96
	s_mov_b32 s6, 0xf620000
	s_nop 0
	v_addc_co_u32_e32 v103, vcc, 0, v97, vcc
	v_mfma_f32_16x16x32_bf16 v[80:83], v[104:107], v[120:123], v[80:83]
	v_lshl_add_u64 v[98:99], v[164:165], 0, s[2:3]
	s_add_u32 s2, s2, 0x80
	s_addc_u32 s3, s3, 0
	v_mfma_f32_16x16x32_bf16 v[72:75], v[104:107], v[132:135], v[72:75]
	s_cmpk_eq_i32 s2, 0x780
	v_mfma_f32_16x16x32_bf16 v[60:63], v[104:107], v[208:211], v[60:63]
	v_mfma_f32_16x16x32_bf16 v[56:59], v[104:107], v[136:139], v[56:59]
	v_add_co_u32_e32 v104, vcc, s6, v96
	s_mov_b32 s6, 0xf630000
	s_nop 0
	v_addc_co_u32_e32 v105, vcc, 0, v97, vcc
	v_add_co_u32_e32 v108, vcc, s6, v96
	s_mov_b32 s6, 0xf640000
	s_nop 0
	v_addc_co_u32_e32 v109, vcc, 0, v97, vcc
	v_add_co_u32_e32 v112, vcc, s6, v96
	s_mov_b32 s6, 0xf650000
	s_nop 0
	v_addc_co_u32_e32 v113, vcc, 0, v97, vcc
	v_add_co_u32_e32 v116, vcc, s6, v96
	s_mov_b32 s6, 0x11c80000
	s_nop 0
	v_addc_co_u32_e32 v117, vcc, 0, v97, vcc
	v_mfma_f32_16x16x32_bf16 v[52:55], v[124:127], v[120:123], v[52:55]
	v_mfma_f32_16x16x32_bf16 v[48:51], v[124:127], v[132:135], v[48:51]
	v_mfma_f32_16x16x32_bf16 v[36:39], v[124:127], v[208:211], v[36:39]
	v_mfma_f32_16x16x32_bf16 v[24:27], v[124:127], v[136:139], v[24:27]
	v_add_co_u32_e32 v124, vcc, s6, v98
	s_mov_b32 s6, 0x11c90000
	s_nop 0
	v_addc_co_u32_e32 v125, vcc, 0, v99, vcc
	v_add_co_u32_e32 v126, vcc, s6, v98
	s_mov_b32 s6, 0x11ca0000
	s_nop 0
	v_addc_co_u32_e32 v127, vcc, 0, v99, vcc
	v_mfma_f32_16x16x32_bf16 v[8:11], v[128:131], v[120:123], v[8:11]
	v_mfma_f32_16x16x32_bf16 v[0:3], v[128:131], v[132:135], v[0:3]
	v_mfma_f32_16x16x32_bf16 v[12:15], v[128:131], v[208:211], v[12:15]
	v_mfma_f32_16x16x32_bf16 v[20:23], v[128:131], v[136:139], v[20:23]
	v_add_co_u32_e32 v128, vcc, s6, v98
	s_mov_b32 s6, 0x11cb0000
	s_nop 0
	v_addc_co_u32_e32 v129, vcc, 0, v99, vcc
	v_mfma_f32_16x16x32_bf16 v[4:7], v[212:215], v[120:123], v[4:7]
	v_mfma_f32_16x16x32_bf16 v[16:19], v[212:215], v[132:135], v[16:19]
	v_mfma_f32_16x16x32_bf16 v[32:35], v[212:215], v[208:211], v[32:35]
	v_mfma_f32_16x16x32_bf16 v[44:47], v[212:215], v[136:139], v[44:47]
	v_add_co_u32_e32 v212, vcc, s6, v98
	v_mfma_f32_16x16x32_bf16 v[28:31], v[216:219], v[120:123], v[28:31]
	s_nop 0
	v_addc_co_u32_e32 v213, vcc, 0, v99, vcc
	global_load_dwordx4 v[96:99], v[100:101], off offset:128
	s_nop 0
	global_load_dwordx4 v[100:103], v[102:103], off offset:128
	s_nop 0
	global_load_dwordx4 v[104:107], v[104:105], off offset:128
	s_nop 0
	global_load_dwordx4 v[108:111], v[108:109], off offset:128
	s_nop 0
	global_load_dwordx4 v[112:115], v[112:113], off offset:128
	s_nop 0
	global_load_dwordx4 v[116:119], v[116:117], off offset:128
	s_waitcnt lgkmcnt(0)
	v_mfma_f32_16x16x32_bf16 v[76:79], v[140:143], v[120:123], v[76:79]
	global_load_dwordx4 v[120:123], v[124:125], off offset:128
	s_nop 0
	global_load_dwordx4 v[124:127], v[126:127], off offset:128
	s_nop 0
	global_load_dwordx4 v[128:131], v[128:129], off offset:128
	v_mfma_f32_16x16x32_bf16 v[40:43], v[216:219], v[132:135], v[40:43]
	v_mfma_f32_16x16x32_bf16 v[68:71], v[140:143], v[132:135], v[68:71]
	global_load_dwordx4 v[132:135], v[212:213], off offset:128
	s_barrier
	v_mfma_f32_16x16x32_bf16 v[88:91], v[216:219], v[208:211], v[88:91]
	v_mfma_f32_16x16x32_bf16 v[84:87], v[216:219], v[136:139], v[84:87]
	v_mfma_f32_16x16x32_bf16 v[64:67], v[140:143], v[208:211], v[64:67]
	v_mfma_f32_16x16x32_bf16 v[92:95], v[140:143], v[136:139], v[92:95]
	s_cbranch_scc0 .LBB0_1137
	s_waitcnt vmcnt(9)
	ds_write_b128 v204, v[96:99]
	s_waitcnt vmcnt(8)
	ds_write_b128 v204, v[100:103] offset:4608
	s_waitcnt vmcnt(7)
	ds_write_b128 v204, v[104:107] offset:9216
	s_waitcnt vmcnt(6)
	ds_write_b128 v204, v[108:111] offset:13824
	s_waitcnt vmcnt(5)
	ds_write_b128 v204, v[112:115] offset:18432
	s_waitcnt vmcnt(4)
	ds_write_b128 v204, v[116:119] offset:23040
	s_waitcnt vmcnt(3)
	ds_write_b128 v204, v[120:123] offset:27648
	s_waitcnt vmcnt(2)
	ds_write_b128 v204, v[124:127] offset:32256
	s_waitcnt vmcnt(1)
	ds_write_b128 v204, v[128:131] offset:36864
	s_waitcnt vmcnt(0)
	ds_write_b128 v204, v[132:135] offset:41472
	s_waitcnt lgkmcnt(0)
	s_barrier
	ds_read_b128 v[96:99], v205 offset:27648
	ds_read_b128 v[100:103], v205 offset:29952
	ds_read_b128 v[104:107], v205 offset:32256
	ds_read_b128 v[108:111], v205 offset:34560
	ds_read_b128 v[112:115], v206
	s_waitcnt lgkmcnt(0)
	v_mfma_f32_16x16x32_bf16 v[80:83], v[112:115], v[96:99], v[80:83]
	v_readlane_b32 s8, v251, 45
	s_movk_i32 s6, 0x1000
	v_readlane_b32 s9, v251, 46
	v_mfma_f32_16x16x32_bf16 v[72:75], v[112:115], v[100:103], v[72:75]
	v_readlane_b32 s10, v251, 47
	v_readlane_b32 s11, v251, 48
	v_mov_b32_e32 v161, v149
	v_mfma_f32_16x16x32_bf16 v[60:63], v[112:115], v[104:107], v[60:63]
	v_readlane_b32 s12, v251, 49
	v_readlane_b32 s14, v251, 51
	v_readlane_b32 s15, v251, 52
	v_mfma_f32_16x16x32_bf16 v[56:59], v[112:115], v[108:111], v[56:59]
	ds_read_b128 v[112:115], v206 offset:2304
	s_mov_b64 s[14:15], 0x12482000
	s_mov_b32 s12, 0x12482000
	s_waitcnt lgkmcnt(0)
	v_mfma_f32_16x16x32_bf16 v[52:55], v[112:115], v[96:99], v[52:55]
	s_movk_i32 s53, 0x1000
	v_readlane_b32 s13, v251, 50
	v_readlane_b32 s16, v251, 53
	v_mfma_f32_16x16x32_bf16 v[48:51], v[112:115], v[100:103], v[48:51]
	v_readlane_b32 s17, v251, 54
	v_readlane_b32 s18, v251, 55
	v_readlane_b32 s19, v251, 56
	v_mfma_f32_16x16x32_bf16 v[36:39], v[112:115], v[104:107], v[36:39]
	v_readlane_b32 s20, v251, 57
	v_readlane_b32 s21, v251, 58
	v_readlane_b32 s22, v251, 59
	v_mfma_f32_16x16x32_bf16 v[24:27], v[112:115], v[108:111], v[24:27]
	ds_read_b128 v[112:115], v206 offset:4608
	v_readlane_b32 s23, v251, 60
	s_waitcnt lgkmcnt(0)
	v_mfma_f32_16x16x32_bf16 v[8:11], v[112:115], v[96:99], v[8:11]
	v_mfma_f32_16x16x32_bf16 v[0:3], v[112:115], v[100:103], v[0:3]
	v_mfma_f32_16x16x32_bf16 v[12:15], v[112:115], v[104:107], v[12:15]
	v_mfma_f32_16x16x32_bf16 v[20:23], v[112:115], v[108:111], v[20:23]
	ds_read_b128 v[112:115], v206 offset:6912
	s_waitcnt lgkmcnt(0)
	v_mfma_f32_16x16x32_bf16 v[4:7], v[112:115], v[96:99], v[4:7]
	v_mfma_f32_16x16x32_bf16 v[16:19], v[112:115], v[100:103], v[16:19]
	v_mfma_f32_16x16x32_bf16 v[32:35], v[112:115], v[104:107], v[32:35]
	v_mfma_f32_16x16x32_bf16 v[112:115], v[112:115], v[108:111], v[44:47]
	s_nop 2
	ds_read_b128 v[44:47], v206 offset:9216
	s_waitcnt lgkmcnt(0)
	v_mfma_f32_16x16x32_bf16 v[116:119], v[44:47], v[100:103], v[40:43]
	s_nop 2
	ds_read_b128 v[40:43], v206 offset:11520
	v_mfma_f32_16x16x32_bf16 v[28:31], v[44:47], v[96:99], v[28:31]
	v_mfma_f32_16x16x32_bf16 v[120:123], v[44:47], v[104:107], v[88:91]
	v_mfma_f32_16x16x32_bf16 v[124:127], v[44:47], v[108:111], v[84:87]
	s_waitcnt lgkmcnt(0)
	v_mfma_f32_16x16x32_bf16 v[96:99], v[40:43], v[96:99], v[76:79]
	v_mfma_f32_16x16x32_bf16 v[100:103], v[40:43], v[100:103], v[68:71]
	v_mfma_f32_16x16x32_bf16 v[104:107], v[40:43], v[104:107], v[64:67]
	v_mfma_f32_16x16x32_bf16 v[108:111], v[40:43], v[108:111], v[92:95]
	ds_read_b128 v[128:131], v205 offset:27712
	ds_read_b128 v[132:135], v205 offset:30016
	ds_read_b128 v[136:139], v205 offset:32320
	ds_read_b128 v[140:143], v205 offset:34624
	ds_read_b128 v[40:43], v206 offset:64
	s_waitcnt lgkmcnt(0)
	v_mfma_f32_16x16x32_bf16 v[92:95], v[40:43], v[128:131], v[80:83]
	v_mfma_f32_16x16x32_bf16 v[88:91], v[40:43], v[132:135], v[72:75]
	v_mfma_f32_16x16x32_bf16 v[84:87], v[40:43], v[136:139], v[60:63]
	v_mfma_f32_16x16x32_bf16 v[80:83], v[40:43], v[140:143], v[56:59]
	ds_read_b128 v[40:43], v206 offset:2368
	s_waitcnt lgkmcnt(0)
	v_mfma_f32_16x16x32_bf16 v[64:67], v[40:43], v[140:143], v[24:27]
	s_nop 2
	ds_read_b128 v[24:27], v206 offset:4672
	s_waitcnt lgkmcnt(0)
	v_mfma_f32_16x16x32_bf16 v[56:59], v[24:27], v[132:135], v[0:3]
	s_nop 2
	ds_read_b128 v[0:3], v206 offset:6976
	v_mfma_f32_16x16x32_bf16 v[76:79], v[40:43], v[128:131], v[52:55]
	v_mfma_f32_16x16x32_bf16 v[72:75], v[40:43], v[132:135], v[48:51]
	v_mfma_f32_16x16x32_bf16 v[68:71], v[40:43], v[136:139], v[36:39]
	s_waitcnt lgkmcnt(0)
	v_mfma_f32_16x16x32_bf16 v[44:47], v[0:3], v[128:131], v[4:7]
	v_mfma_f32_16x16x32_bf16 v[40:43], v[0:3], v[132:135], v[16:19]
	v_mfma_f32_16x16x32_bf16 v[36:39], v[0:3], v[136:139], v[32:35]
	v_mfma_f32_16x16x32_bf16 v[32:35], v[0:3], v[140:143], v[112:115]
	ds_read_b128 v[0:3], v206 offset:9280
	v_mfma_f32_16x16x32_bf16 v[60:63], v[24:27], v[128:131], v[8:11]
	v_mfma_f32_16x16x32_bf16 v[52:55], v[24:27], v[136:139], v[12:15]
	v_mfma_f32_16x16x32_bf16 v[48:51], v[24:27], v[140:143], v[20:23]
	s_waitcnt lgkmcnt(0)
	v_mfma_f32_16x16x32_bf16 v[28:31], v[0:3], v[128:131], v[28:31]
	v_mfma_f32_16x16x32_bf16 v[24:27], v[0:3], v[132:135], v[116:119]
	v_mfma_f32_16x16x32_bf16 v[20:23], v[0:3], v[136:139], v[120:123]
	v_mfma_f32_16x16x32_bf16 v[16:19], v[0:3], v[140:143], v[124:127]
	ds_read_b128 v[0:3], v206 offset:11584
	s_waitcnt lgkmcnt(0)
	s_barrier
	v_mfma_f32_16x16x32_bf16 v[12:15], v[0:3], v[128:131], v[96:99]
	s_nop 2
	v_add_u32_e32 v98, s1, v166
	s_ashr_i32 s1, s0, 31
	v_add_u32_e32 v97, 0xfffff000, v98
	s_lshl_b64 s[0:1], s[0:1], 2
	v_or_b32_e32 v96, v98, v167
	v_lshrrev_b32_e32 v97, 12, v97
	v_mfma_f32_16x16x32_bf16 v[4:7], v[0:3], v[136:139], v[104:107]
	s_add_u32 s2, s82, s0
	v_add_u32_e32 v99, 1, v97
	v_ashrrev_i32_e32 v97, 31, v96
	v_add_u32_e32 v106, 0xfffff000, v96
	v_mov_b32_e32 v107, v149
	v_mfma_f32_16x16x32_bf16 v[8:11], v[0:3], v[132:135], v[100:103]
	s_addc_u32 s3, s83, s1
	v_lshlrev_b64 v[106:107], 12, v[106:107]
	v_cmp_gt_i32_e32 vcc, s6, v96
	v_lshlrev_b64 v[100:101], 12, v[96:97]
	v_lshl_add_u64 v[102:103], s[2:3], 0, v[100:101]
	v_lshl_add_u64 v[100:101], s[8:9], 0, v[100:101]
	v_lshl_add_u64 v[106:107], s[10:11], 0, v[106:107]
	v_cndmask_b32_e32 v101, v107, v101, vcc
	v_cndmask_b32_e32 v100, v106, v100, vcc
	v_cndmask_b32_e64 v97, v99, 0, vcc
	v_lshl_add_u64 v[100:101], v[100:101], 0, s[0:1]
	v_add_u32_e32 v97, s4, v97
	v_lshl_add_u64 v[104:105], v[102:103], 0, v[148:149]
	v_cndmask_b32_e64 v100, v102, v100, s[36:37]
	v_mul_lo_u32 v102, v97, s24
	v_cndmask_b32_e64 v101, v103, v101, s[36:37]
	v_ashrrev_i32_e32 v103, 31, v102
	v_lshl_add_u64 v[102:103], v[102:103], 2, s[82:83]
	v_lshl_add_u64 v[102:103], v[102:103], 0, s[0:1]
	v_lshl_add_u64 v[102:103], v[102:103], 0, v[148:149]
	v_lshl_add_u64 v[102:103], v[102:103], 0, v[160:161]
	v_lshl_add_u64 v[106:107], v[102:103], 0, s[14:15]
	v_lshl_add_u64 v[100:101], v[100:101], 0, v[148:149]
	v_add_co_u32_e32 v102, vcc, s12, v102
	v_lshl_add_u64 v[100:101], v[100:101], 0, v[160:161]
	s_nop 0
	v_addc_co_u32_e32 v103, vcc, 0, v103, vcc
	global_load_dword v112, v[100:101], off
	v_lshl_add_u64 v[104:105], v[104:105], 0, v[160:161]
	global_load_dword v116, v[102:103], off
	v_mfma_f32_16x16x32_bf16 v[0:3], v[0:3], v[140:143], v[108:111]
	s_add_i32 s5, s5, s92
	s_cmp_ge_i32 s5, s93
	global_load_dword v113, v[100:101], off offset:64
	global_load_dword v117, v[106:107], off offset:64
	global_load_dword v114, v[100:101], off offset:128
	global_load_dword v118, v[106:107], off offset:128
	global_load_dword v115, v[100:101], off offset:192
	global_load_dword v119, v[106:107], off offset:192
	v_mov_b32_e32 v120, v92
	v_mov_b32_e32 v121, v88
	v_mov_b32_e32 v122, v84
	v_mov_b32_e32 v123, v80
	v_mov_b64_e32 v[124:125], v[104:105]
	v_or_b32_e32 v100, 1, v96
	v_ashrrev_i32_e32 v101, 31, v100
	v_lshlrev_b64 v[102:103], 12, v[100:101]
	v_cmp_gt_i32_e32 vcc, s6, v100
	v_lshl_add_u64 v[100:101], s[8:9], 0, v[102:103]
	v_lshl_add_u64 v[104:105], s[2:3], 0, v[102:103]
	v_add_u32_e32 v102, 0xfffff001, v96
	v_mov_b32_e32 v103, v149
	v_lshlrev_b64 v[102:103], 12, v[102:103]
	v_cndmask_b32_e64 v80, v99, 0, vcc
	v_lshl_add_u64 v[102:103], s[10:11], 0, v[102:103]
	v_add_u32_e32 v80, s4, v80
	v_cndmask_b32_e32 v100, v102, v100, vcc
	v_mul_lo_u32 v102, v80, s24
	v_cndmask_b32_e32 v101, v103, v101, vcc
	v_ashrrev_i32_e32 v103, 31, v102
	v_lshl_add_u64 v[102:103], v[102:103], 2, s[82:83]
	v_lshl_add_u64 v[102:103], v[102:103], 0, s[0:1]
	v_lshl_add_u64 v[100:101], v[100:101], 0, s[0:1]
	v_lshl_add_u64 v[102:103], v[102:103], 0, v[148:149]
	v_cndmask_b32_e64 v101, v105, v101, s[36:37]
	v_cndmask_b32_e64 v100, v104, v100, s[36:37]
	v_lshl_add_u64 v[102:103], v[102:103], 0, v[160:161]
	v_lshl_add_u64 v[106:107], v[104:105], 0, v[148:149]
	v_lshl_add_u64 v[104:105], v[102:103], 0, s[14:15]
	v_lshl_add_u64 v[100:101], v[100:101], 0, v[148:149]
	v_add_co_u32_e32 v102, vcc, s12, v102
	v_lshl_add_u64 v[100:101], v[100:101], 0, v[160:161]
	s_nop 0
	v_addc_co_u32_e32 v103, vcc, 0, v103, vcc
	global_load_dword v126, v[100:101], off
	global_load_dword v130, v[102:103], off
	v_lshl_add_u64 v[106:107], v[106:107], 0, v[160:161]
	global_load_dword v127, v[100:101], off offset:64
	global_load_dword v131, v[104:105], off offset:64
	global_load_dword v128, v[100:101], off offset:128
	global_load_dword v132, v[104:105], off offset:128
	global_load_dword v129, v[100:101], off offset:192
	global_load_dword v133, v[104:105], off offset:192
	v_mov_b32_e32 v134, v93
	v_mov_b32_e32 v135, v89
	v_mov_b32_e32 v136, v85
	v_mov_b32_e32 v137, v81
	v_mov_b64_e32 v[138:139], v[106:107]
	v_or_b32_e32 v80, 2, v96
	v_ashrrev_i32_e32 v81, 31, v80
	v_lshlrev_b64 v[84:85], 12, v[80:81]
	v_lshl_add_u64 v[88:89], s[2:3], 0, v[84:85]
	v_cmp_gt_i32_e32 vcc, s6, v80
	v_lshl_add_u64 v[80:81], s[8:9], 0, v[84:85]
	v_add_u32_e32 v84, 0xfffff002, v96
	v_mov_b32_e32 v85, v149
	v_lshlrev_b64 v[84:85], 12, v[84:85]
	v_lshl_add_u64 v[84:85], s[10:11], 0, v[84:85]
	v_cndmask_b32_e32 v80, v84, v80, vcc
	v_cndmask_b32_e64 v84, v99, 0, vcc
	v_add_u32_e32 v84, s4, v84
	v_mul_lo_u32 v84, v84, s24
	v_cndmask_b32_e32 v81, v85, v81, vcc
	v_ashrrev_i32_e32 v85, 31, v84
	v_lshl_add_u64 v[84:85], v[84:85], 2, s[82:83]
	v_lshl_add_u64 v[84:85], v[84:85], 0, s[0:1]
	v_lshl_add_u64 v[80:81], v[80:81], 0, s[0:1]
	v_lshl_add_u64 v[84:85], v[84:85], 0, v[148:149]
	v_cndmask_b32_e64 v81, v89, v81, s[36:37]
	v_cndmask_b32_e64 v80, v88, v80, s[36:37]
	v_lshl_add_u64 v[84:85], v[84:85], 0, v[160:161]
	v_lshl_add_u64 v[92:93], v[88:89], 0, v[148:149]
	v_lshl_add_u64 v[88:89], v[84:85], 0, s[14:15]
	v_lshl_add_u64 v[80:81], v[80:81], 0, v[148:149]
	v_add_co_u32_e32 v84, vcc, s12, v84
	v_lshl_add_u64 v[80:81], v[80:81], 0, v[160:161]
	s_nop 0
	v_addc_co_u32_e32 v85, vcc, 0, v85, vcc
	global_load_dword v234, v[80:81], off
	v_lshl_add_u64 v[92:93], v[92:93], 0, v[160:161]
	global_load_dword v238, v[84:85], off
	global_load_dword v235, v[80:81], off offset:64
	global_load_dword v239, v[88:89], off offset:64
	global_load_dword v236, v[80:81], off offset:128
	global_load_dword v240, v[88:89], off offset:128
	global_load_dword v237, v[80:81], off offset:192
	global_load_dword v241, v[88:89], off offset:192
	v_mov_b32_e32 v242, v94
	v_mov_b32_e32 v243, v90
	v_mov_b32_e32 v244, v86
	v_mov_b32_e32 v245, v82
	v_mov_b64_e32 v[220:221], v[92:93]
	s_waitcnt vmcnt(16)
	v_fmac_f32_e32 v112, v120, v116
	v_fmac_f32_e32 v113, v121, v117
	v_fmac_f32_e32 v114, v122, v118
	v_fmac_f32_e32 v115, v123, v119
	global_store_dword v[124:125], v112, off
	global_store_dword v[124:125], v113, off offset:64
	global_store_dword v[124:125], v114, off offset:128
	global_store_dword v[124:125], v115, off offset:192
	v_or_b32_e32 v80, 3, v96
	v_ashrrev_i32_e32 v81, 31, v80
	v_lshlrev_b64 v[84:85], 12, v[80:81]
	v_lshl_add_u64 v[88:89], s[2:3], 0, v[84:85]
	v_cmp_gt_i32_e32 vcc, s6, v80
	v_lshl_add_u64 v[80:81], s[8:9], 0, v[84:85]
	v_add_u32_e32 v84, 0xfffff003, v96
	v_mov_b32_e32 v85, v149
	v_lshlrev_b64 v[84:85], 12, v[84:85]
	v_cndmask_b32_e64 v82, v99, 0, vcc
	v_lshl_add_u64 v[84:85], s[10:11], 0, v[84:85]
	v_add_u32_e32 v82, s4, v82
	v_cndmask_b32_e32 v80, v84, v80, vcc
	v_mul_lo_u32 v84, v82, s24
	v_cndmask_b32_e32 v81, v85, v81, vcc
	v_ashrrev_i32_e32 v85, 31, v84
	v_lshl_add_u64 v[84:85], v[84:85], 2, s[82:83]
	v_lshl_add_u64 v[84:85], v[84:85], 0, s[0:1]
	v_lshl_add_u64 v[80:81], v[80:81], 0, s[0:1]
	v_lshl_add_u64 v[84:85], v[84:85], 0, v[148:149]
	v_cndmask_b32_e64 v81, v89, v81, s[36:37]
	v_cndmask_b32_e64 v80, v88, v80, s[36:37]
	v_lshl_add_u64 v[84:85], v[84:85], 0, v[160:161]
	v_lshl_add_u64 v[92:93], v[88:89], 0, v[148:149]
	v_lshl_add_u64 v[88:89], v[84:85], 0, s[14:15]
	v_lshl_add_u64 v[80:81], v[80:81], 0, v[148:149]
	v_add_co_u32_e32 v84, vcc, s12, v84
	v_lshl_add_u64 v[80:81], v[80:81], 0, v[160:161]
	s_nop 0
	v_addc_co_u32_e32 v85, vcc, 0, v85, vcc
	global_load_dword v112, v[80:81], off
	v_lshl_add_u64 v[92:93], v[92:93], 0, v[160:161]
	global_load_dword v116, v[84:85], off
	global_load_dword v113, v[80:81], off offset:64
	global_load_dword v117, v[88:89], off offset:64
	global_load_dword v114, v[80:81], off offset:128
	global_load_dword v118, v[88:89], off offset:128
	global_load_dword v115, v[80:81], off offset:192
	global_load_dword v119, v[88:89], off offset:192
	v_mov_b32_e32 v120, v95
	v_mov_b32_e32 v121, v91
	v_mov_b32_e32 v122, v87
	v_mov_b32_e32 v123, v83
	v_mov_b64_e32 v[124:125], v[92:93]
	s_waitcnt vmcnt(20)
	v_fmac_f32_e32 v126, v134, v130
	v_fmac_f32_e32 v127, v135, v131
	v_fmac_f32_e32 v128, v136, v132
	v_fmac_f32_e32 v129, v137, v133
	global_store_dword v[138:139], v126, off
	global_store_dword v[138:139], v127, off offset:64
	global_store_dword v[138:139], v128, off offset:128
	global_store_dword v[138:139], v129, off offset:192
	v_or_b32_e32 v84, 16, v96
	v_ashrrev_i32_e32 v85, 31, v84
	v_lshlrev_b64 v[86:87], 12, v[84:85]
	v_lshl_add_u64 v[88:89], s[2:3], 0, v[86:87]
	v_cmp_gt_i32_e32 vcc, s6, v84
	v_lshl_add_u64 v[84:85], s[8:9], 0, v[86:87]
	v_add_u32_e32 v86, 0xfffff010, v96
	v_mov_b32_e32 v87, v149
	v_lshlrev_b64 v[86:87], 12, v[86:87]
	v_lshl_add_u64 v[86:87], s[10:11], 0, v[86:87]
	v_cndmask_b32_e32 v84, v86, v84, vcc
	v_cndmask_b32_e32 v85, v87, v85, vcc
	v_lshl_add_u64 v[84:85], v[84:85], 0, s[0:1]
	v_cndmask_b32_e64 v85, v89, v85, s[36:37]
	v_cndmask_b32_e64 v84, v88, v84, s[36:37]
	v_lshl_add_u64 v[84:85], v[84:85], 0, v[148:149]
	v_lshl_add_u64 v[84:85], v[84:85], 0, v[160:161]
	v_add_u32_e32 v80, 0xfffff010, v98
	v_lshrrev_b32_e32 v80, 12, v80
	v_add_u32_e32 v82, 1, v80
	v_cndmask_b32_e64 v83, v82, 0, vcc
	v_add_u32_e32 v83, s4, v83
	v_mul_lo_u32 v86, v83, s24
	v_ashrrev_i32_e32 v87, 31, v86
	v_lshl_add_u64 v[86:87], v[86:87], 2, s[82:83]
	v_lshl_add_u64 v[86:87], v[86:87], 0, s[0:1]
	v_lshl_add_u64 v[86:87], v[86:87], 0, v[148:149]
	v_lshl_add_u64 v[86:87], v[86:87], 0, v[160:161]
	v_lshl_add_u64 v[80:81], v[88:89], 0, v[148:149]
	v_lshl_add_u64 v[88:89], v[86:87], 0, s[14:15]
	v_add_co_u32_e32 v86, vcc, s12, v86
	global_load_dword v126, v[84:85], off
	s_nop 0
	v_addc_co_u32_e32 v87, vcc, 0, v87, vcc
	global_load_dword v130, v[86:87], off
	v_lshl_add_u64 v[80:81], v[80:81], 0, v[160:161]
	global_load_dword v127, v[84:85], off offset:64
	global_load_dword v131, v[88:89], off offset:64
	global_load_dword v128, v[84:85], off offset:128
	global_load_dword v132, v[88:89], off offset:128
	global_load_dword v129, v[84:85], off offset:192
	global_load_dword v133, v[88:89], off offset:192
	v_mov_b32_e32 v134, v76
	v_mov_b32_e32 v135, v72
	v_mov_b32_e32 v136, v68
	v_mov_b32_e32 v137, v64
	v_mov_b64_e32 v[138:139], v[80:81]
	s_waitcnt vmcnt(24)
	v_fmac_f32_e32 v234, v242, v238
	v_fmac_f32_e32 v235, v243, v239
	v_fmac_f32_e32 v236, v244, v240
	v_fmac_f32_e32 v237, v245, v241
	global_store_dword v[220:221], v234, off
	global_store_dword v[220:221], v235, off offset:64
	global_store_dword v[220:221], v236, off offset:128
	global_store_dword v[220:221], v237, off offset:192
	v_or_b32_e32 v80, 17, v96
	v_ashrrev_i32_e32 v81, 31, v80
	v_lshlrev_b64 v[84:85], 12, v[80:81]
	v_lshl_add_u64 v[86:87], s[2:3], 0, v[84:85]
	v_cmp_gt_i32_e32 vcc, s6, v80
	v_lshl_add_u64 v[80:81], s[8:9], 0, v[84:85]
	v_add_u32_e32 v84, 0xfffff011, v96
	v_mov_b32_e32 v85, v149
	v_lshlrev_b64 v[84:85], 12, v[84:85]
	v_cndmask_b32_e64 v64, v82, 0, vcc
	v_lshl_add_u64 v[84:85], s[10:11], 0, v[84:85]
	v_add_u32_e32 v64, s4, v64
	v_cndmask_b32_e32 v80, v84, v80, vcc
	v_mul_lo_u32 v84, v64, s24
	v_cndmask_b32_e32 v81, v85, v81, vcc
	v_ashrrev_i32_e32 v85, 31, v84
	v_lshl_add_u64 v[84:85], v[84:85], 2, s[82:83]
	v_lshl_add_u64 v[84:85], v[84:85], 0, s[0:1]
	v_lshl_add_u64 v[80:81], v[80:81], 0, s[0:1]
	v_lshl_add_u64 v[84:85], v[84:85], 0, v[148:149]
	v_cndmask_b32_e64 v81, v87, v81, s[36:37]
	v_cndmask_b32_e64 v80, v86, v80, s[36:37]
	v_lshl_add_u64 v[84:85], v[84:85], 0, v[160:161]
	v_lshl_add_u64 v[88:89], v[86:87], 0, v[148:149]
	v_lshl_add_u64 v[86:87], v[84:85], 0, s[14:15]
	v_lshl_add_u64 v[80:81], v[80:81], 0, v[148:149]
	v_add_co_u32_e32 v84, vcc, s12, v84
	v_lshl_add_u64 v[80:81], v[80:81], 0, v[160:161]
	s_nop 0
	v_addc_co_u32_e32 v85, vcc, 0, v85, vcc
	global_load_dword v234, v[80:81], off
	global_load_dword v238, v[84:85], off
	v_lshl_add_u64 v[88:89], v[88:89], 0, v[160:161]
	global_load_dword v235, v[80:81], off offset:64
	global_load_dword v239, v[86:87], off offset:64
	global_load_dword v236, v[80:81], off offset:128
	global_load_dword v240, v[86:87], off offset:128
	global_load_dword v237, v[80:81], off offset:192
	global_load_dword v241, v[86:87], off offset:192
	v_mov_b32_e32 v242, v77
	v_mov_b32_e32 v243, v73
	v_mov_b32_e32 v244, v69
	v_mov_b32_e32 v245, v65
	v_mov_b64_e32 v[220:221], v[88:89]
	s_waitcnt vmcnt(24)
	v_fmac_f32_e32 v112, v120, v116
	v_fmac_f32_e32 v113, v121, v117
	v_fmac_f32_e32 v114, v122, v118
	v_fmac_f32_e32 v115, v123, v119
	global_store_dword v[124:125], v112, off
	global_store_dword v[124:125], v113, off offset:64
	global_store_dword v[124:125], v114, off offset:128
	global_store_dword v[124:125], v115, off offset:192
	v_or_b32_e32 v64, 18, v96
	v_ashrrev_i32_e32 v65, 31, v64
	v_lshlrev_b64 v[68:69], 12, v[64:65]
	v_lshl_add_u64 v[72:73], s[2:3], 0, v[68:69]
	v_cmp_gt_i32_e32 vcc, s6, v64
	v_lshl_add_u64 v[64:65], s[8:9], 0, v[68:69]
	v_add_u32_e32 v68, 0xfffff012, v96
	v_mov_b32_e32 v69, v149
	v_lshlrev_b64 v[68:69], 12, v[68:69]
	v_lshl_add_u64 v[68:69], s[10:11], 0, v[68:69]
	v_cndmask_b32_e32 v64, v68, v64, vcc
	v_cndmask_b32_e64 v68, v82, 0, vcc
	v_add_u32_e32 v68, s4, v68
	v_mul_lo_u32 v68, v68, s24
	v_cndmask_b32_e32 v65, v69, v65, vcc
	v_ashrrev_i32_e32 v69, 31, v68
	v_lshl_add_u64 v[68:69], v[68:69], 2, s[82:83]
	v_lshl_add_u64 v[68:69], v[68:69], 0, s[0:1]
	v_lshl_add_u64 v[64:65], v[64:65], 0, s[0:1]
	v_lshl_add_u64 v[68:69], v[68:69], 0, v[148:149]
	v_cndmask_b32_e64 v65, v73, v65, s[36:37]
	v_cndmask_b32_e64 v64, v72, v64, s[36:37]
	v_lshl_add_u64 v[68:69], v[68:69], 0, v[160:161]
	v_lshl_add_u64 v[76:77], v[72:73], 0, v[148:149]
	v_lshl_add_u64 v[72:73], v[68:69], 0, s[14:15]
	v_lshl_add_u64 v[64:65], v[64:65], 0, v[148:149]
	v_add_co_u32_e32 v68, vcc, s12, v68
	v_lshl_add_u64 v[64:65], v[64:65], 0, v[160:161]
	s_nop 0
	v_addc_co_u32_e32 v69, vcc, 0, v69, vcc
	global_load_dword v112, v[64:65], off
	v_lshl_add_u64 v[76:77], v[76:77], 0, v[160:161]
	global_load_dword v116, v[68:69], off
	global_load_dword v113, v[64:65], off offset:64
	global_load_dword v117, v[72:73], off offset:64
	global_load_dword v114, v[64:65], off offset:128
	global_load_dword v118, v[72:73], off offset:128
	global_load_dword v115, v[64:65], off offset:192
	global_load_dword v119, v[72:73], off offset:192
	v_mov_b32_e32 v120, v78
	v_mov_b32_e32 v121, v74
	v_mov_b32_e32 v122, v70
	v_mov_b32_e32 v123, v66
	v_mov_b64_e32 v[124:125], v[76:77]
	s_waitcnt vmcnt(24)
	v_fmac_f32_e32 v126, v134, v130
	v_fmac_f32_e32 v127, v135, v131
	v_fmac_f32_e32 v128, v136, v132
	v_fmac_f32_e32 v129, v137, v133
	global_store_dword v[138:139], v126, off
	global_store_dword v[138:139], v127, off offset:64
	global_store_dword v[138:139], v128, off offset:128
	global_store_dword v[138:139], v129, off offset:192
	v_or_b32_e32 v64, 19, v96
	v_ashrrev_i32_e32 v65, 31, v64
	v_lshlrev_b64 v[68:69], 12, v[64:65]
	v_lshl_add_u64 v[72:73], s[2:3], 0, v[68:69]
	v_cmp_gt_i32_e32 vcc, s6, v64
	v_lshl_add_u64 v[64:65], s[8:9], 0, v[68:69]
	v_add_u32_e32 v68, 0xfffff013, v96
	v_mov_b32_e32 v69, v149
	v_lshlrev_b64 v[68:69], 12, v[68:69]
	v_cndmask_b32_e64 v66, v82, 0, vcc
	v_lshl_add_u64 v[68:69], s[10:11], 0, v[68:69]
	v_add_u32_e32 v66, s4, v66
	v_cndmask_b32_e32 v64, v68, v64, vcc
	v_mul_lo_u32 v68, v66, s24
	v_cndmask_b32_e32 v65, v69, v65, vcc
	v_ashrrev_i32_e32 v69, 31, v68
	v_lshl_add_u64 v[68:69], v[68:69], 2, s[82:83]
	v_lshl_add_u64 v[68:69], v[68:69], 0, s[0:1]
	v_lshl_add_u64 v[64:65], v[64:65], 0, s[0:1]
	v_lshl_add_u64 v[68:69], v[68:69], 0, v[148:149]
	v_cndmask_b32_e64 v65, v73, v65, s[36:37]
	v_cndmask_b32_e64 v64, v72, v64, s[36:37]
	v_lshl_add_u64 v[68:69], v[68:69], 0, v[160:161]
	v_lshl_add_u64 v[76:77], v[72:73], 0, v[148:149]
	v_lshl_add_u64 v[72:73], v[68:69], 0, s[14:15]
	v_lshl_add_u64 v[64:65], v[64:65], 0, v[148:149]
	v_add_co_u32_e32 v68, vcc, s12, v68
	v_lshl_add_u64 v[64:65], v[64:65], 0, v[160:161]
	s_nop 0
	v_addc_co_u32_e32 v69, vcc, 0, v69, vcc
	global_load_dword v126, v[64:65], off
	v_lshl_add_u64 v[76:77], v[76:77], 0, v[160:161]
	global_load_dword v130, v[68:69], off
	global_load_dword v127, v[64:65], off offset:64
	global_load_dword v131, v[72:73], off offset:64
	global_load_dword v128, v[64:65], off offset:128
	global_load_dword v132, v[72:73], off offset:128
	global_load_dword v129, v[64:65], off offset:192
	global_load_dword v133, v[72:73], off offset:192
	v_mov_b32_e32 v134, v79
	v_mov_b32_e32 v135, v75
	v_mov_b32_e32 v136, v71
	v_mov_b32_e32 v137, v67
	v_mov_b64_e32 v[138:139], v[76:77]
	s_waitcnt vmcnt(24)
	v_fmac_f32_e32 v234, v242, v238
	v_fmac_f32_e32 v235, v243, v239
	v_fmac_f32_e32 v236, v244, v240
	v_fmac_f32_e32 v237, v245, v241
	global_store_dword v[220:221], v234, off
	global_store_dword v[220:221], v235, off offset:64
	global_store_dword v[220:221], v236, off offset:128
	global_store_dword v[220:221], v237, off offset:192
	v_mov_b32_e32 v75, v149
	v_add_u32_e32 v65, 0xfffff020, v98
	v_add_u32_e32 v64, v98, v168
	v_lshrrev_b32_e32 v65, 12, v65
	v_add_u32_e32 v68, 1, v65
	v_ashrrev_i32_e32 v65, 31, v64
	v_add_u32_e32 v74, 0xfffff000, v64
	v_lshlrev_b64 v[70:71], 12, v[64:65]
	v_lshlrev_b64 v[74:75], 12, v[74:75]
	v_lshl_add_u64 v[72:73], s[2:3], 0, v[70:71]
	v_cmp_gt_i32_e32 vcc, s6, v64
	v_lshl_add_u64 v[70:71], s[8:9], 0, v[70:71]
	v_lshl_add_u64 v[74:75], s[10:11], 0, v[74:75]
	v_cndmask_b32_e32 v71, v75, v71, vcc
	v_cndmask_b32_e32 v70, v74, v70, vcc
	v_cndmask_b32_e64 v65, v68, 0, vcc
	v_lshl_add_u64 v[70:71], v[70:71], 0, s[0:1]
	v_add_u32_e32 v65, s4, v65
	v_lshl_add_u64 v[66:67], v[72:73], 0, v[148:149]
	v_cndmask_b32_e64 v70, v72, v70, s[36:37]
	v_mul_lo_u32 v72, v65, s24
	v_cndmask_b32_e64 v71, v73, v71, s[36:37]
	v_ashrrev_i32_e32 v73, 31, v72
	v_lshl_add_u64 v[72:73], v[72:73], 2, s[82:83]
	v_lshl_add_u64 v[72:73], v[72:73], 0, s[0:1]
	v_lshl_add_u64 v[72:73], v[72:73], 0, v[148:149]
	v_lshl_add_u64 v[72:73], v[72:73], 0, v[160:161]
	v_lshl_add_u64 v[74:75], v[72:73], 0, s[14:15]
	v_lshl_add_u64 v[70:71], v[70:71], 0, v[148:149]
	v_add_co_u32_e32 v72, vcc, s12, v72
	v_lshl_add_u64 v[70:71], v[70:71], 0, v[160:161]
	s_nop 0
	v_addc_co_u32_e32 v73, vcc, 0, v73, vcc
	global_load_dword v234, v[70:71], off
	global_load_dword v238, v[72:73], off
	v_lshl_add_u64 v[66:67], v[66:67], 0, v[160:161]
	global_load_dword v235, v[70:71], off offset:64
	global_load_dword v239, v[74:75], off offset:64
	global_load_dword v236, v[70:71], off offset:128
	global_load_dword v240, v[74:75], off offset:128
	global_load_dword v237, v[70:71], off offset:192
	global_load_dword v241, v[74:75], off offset:192
	v_mov_b32_e32 v242, v60
	v_mov_b32_e32 v243, v56
	v_mov_b32_e32 v244, v52
	v_mov_b32_e32 v245, v48
	v_mov_b64_e32 v[220:221], v[66:67]
	s_waitcnt vmcnt(24)
	v_fmac_f32_e32 v112, v120, v116
	v_fmac_f32_e32 v113, v121, v117
	v_fmac_f32_e32 v114, v122, v118
	v_fmac_f32_e32 v115, v123, v119
	global_store_dword v[124:125], v112, off
	global_store_dword v[124:125], v113, off offset:64
	global_store_dword v[124:125], v114, off offset:128
	global_store_dword v[124:125], v115, off offset:192
	v_or_b32_e32 v66, 1, v64
	v_ashrrev_i32_e32 v67, 31, v66
	v_lshlrev_b64 v[70:71], 12, v[66:67]
	v_lshl_add_u64 v[72:73], s[2:3], 0, v[70:71]
	v_cmp_gt_i32_e32 vcc, s6, v66
	v_lshl_add_u64 v[66:67], s[8:9], 0, v[70:71]
	v_add_u32_e32 v70, 0xfffff001, v64
	v_mov_b32_e32 v71, v149
	v_lshlrev_b64 v[70:71], 12, v[70:71]
	v_cndmask_b32_e64 v48, v68, 0, vcc
	v_lshl_add_u64 v[70:71], s[10:11], 0, v[70:71]
	v_add_u32_e32 v48, s4, v48
	v_cndmask_b32_e32 v66, v70, v66, vcc
	v_mul_lo_u32 v70, v48, s24
	v_cndmask_b32_e32 v67, v71, v67, vcc
	v_ashrrev_i32_e32 v71, 31, v70
	v_lshl_add_u64 v[70:71], v[70:71], 2, s[82:83]
	v_lshl_add_u64 v[70:71], v[70:71], 0, s[0:1]
	v_lshl_add_u64 v[66:67], v[66:67], 0, s[0:1]
	v_lshl_add_u64 v[70:71], v[70:71], 0, v[148:149]
	v_cndmask_b32_e64 v67, v73, v67, s[36:37]
	v_cndmask_b32_e64 v66, v72, v66, s[36:37]
	v_lshl_add_u64 v[70:71], v[70:71], 0, v[160:161]
	v_lshl_add_u64 v[74:75], v[72:73], 0, v[148:149]
	v_lshl_add_u64 v[72:73], v[70:71], 0, s[14:15]
	v_lshl_add_u64 v[66:67], v[66:67], 0, v[148:149]
	v_add_co_u32_e32 v70, vcc, s12, v70
	v_lshl_add_u64 v[66:67], v[66:67], 0, v[160:161]
	s_nop 0
	v_addc_co_u32_e32 v71, vcc, 0, v71, vcc
	global_load_dword v112, v[66:67], off
	global_load_dword v116, v[70:71], off
	v_lshl_add_u64 v[74:75], v[74:75], 0, v[160:161]
	global_load_dword v113, v[66:67], off offset:64
	global_load_dword v117, v[72:73], off offset:64
	global_load_dword v114, v[66:67], off offset:128
	global_load_dword v118, v[72:73], off offset:128
	global_load_dword v115, v[66:67], off offset:192
	global_load_dword v119, v[72:73], off offset:192
	v_mov_b32_e32 v120, v61
	v_mov_b32_e32 v121, v57
	v_mov_b32_e32 v122, v53
	v_mov_b32_e32 v123, v49
	v_mov_b64_e32 v[124:125], v[74:75]
	s_waitcnt vmcnt(24)
	v_fmac_f32_e32 v126, v134, v130
	v_fmac_f32_e32 v127, v135, v131
	v_fmac_f32_e32 v128, v136, v132
	v_fmac_f32_e32 v129, v137, v133
	global_store_dword v[138:139], v126, off
	global_store_dword v[138:139], v127, off offset:64
	global_store_dword v[138:139], v128, off offset:128
	global_store_dword v[138:139], v129, off offset:192
	v_or_b32_e32 v48, 2, v64
	v_ashrrev_i32_e32 v49, 31, v48
	v_lshlrev_b64 v[52:53], 12, v[48:49]
	v_lshl_add_u64 v[56:57], s[2:3], 0, v[52:53]
	v_cmp_gt_i32_e32 vcc, s6, v48
	v_lshl_add_u64 v[48:49], s[8:9], 0, v[52:53]
	v_add_u32_e32 v52, 0xfffff002, v64
	v_mov_b32_e32 v53, v149
	v_lshlrev_b64 v[52:53], 12, v[52:53]
	v_lshl_add_u64 v[52:53], s[10:11], 0, v[52:53]
	v_cndmask_b32_e32 v48, v52, v48, vcc
	v_cndmask_b32_e64 v52, v68, 0, vcc
	v_add_u32_e32 v52, s4, v52
	v_mul_lo_u32 v52, v52, s24
	v_cndmask_b32_e32 v49, v53, v49, vcc
	v_ashrrev_i32_e32 v53, 31, v52
	v_lshl_add_u64 v[52:53], v[52:53], 2, s[82:83]
	v_lshl_add_u64 v[52:53], v[52:53], 0, s[0:1]
	v_lshl_add_u64 v[48:49], v[48:49], 0, s[0:1]
	v_lshl_add_u64 v[52:53], v[52:53], 0, v[148:149]
	v_cndmask_b32_e64 v49, v57, v49, s[36:37]
	v_cndmask_b32_e64 v48, v56, v48, s[36:37]
	v_lshl_add_u64 v[52:53], v[52:53], 0, v[160:161]
	v_lshl_add_u64 v[60:61], v[56:57], 0, v[148:149]
	v_lshl_add_u64 v[56:57], v[52:53], 0, s[14:15]
	v_lshl_add_u64 v[48:49], v[48:49], 0, v[148:149]
	v_add_co_u32_e32 v52, vcc, s12, v52
	v_lshl_add_u64 v[48:49], v[48:49], 0, v[160:161]
	s_nop 0
	v_addc_co_u32_e32 v53, vcc, 0, v53, vcc
	global_load_dword v126, v[48:49], off
	v_lshl_add_u64 v[60:61], v[60:61], 0, v[160:161]
	global_load_dword v130, v[52:53], off
	global_load_dword v127, v[48:49], off offset:64
	global_load_dword v131, v[56:57], off offset:64
	global_load_dword v128, v[48:49], off offset:128
	global_load_dword v132, v[56:57], off offset:128
	global_load_dword v129, v[48:49], off offset:192
	global_load_dword v133, v[56:57], off offset:192
	v_mov_b32_e32 v134, v62
	v_mov_b32_e32 v135, v58
	v_mov_b32_e32 v136, v54
	v_mov_b32_e32 v137, v50
	v_mov_b64_e32 v[138:139], v[60:61]
	s_waitcnt vmcnt(24)
	v_fmac_f32_e32 v234, v242, v238
	v_fmac_f32_e32 v235, v243, v239
	v_fmac_f32_e32 v236, v244, v240
	v_fmac_f32_e32 v237, v245, v241
	global_store_dword v[220:221], v234, off
	global_store_dword v[220:221], v235, off offset:64
	global_store_dword v[220:221], v236, off offset:128
	global_store_dword v[220:221], v237, off offset:192
	v_or_b32_e32 v48, 3, v64
	v_ashrrev_i32_e32 v49, 31, v48
	v_lshlrev_b64 v[52:53], 12, v[48:49]
	v_lshl_add_u64 v[56:57], s[2:3], 0, v[52:53]
	v_cmp_gt_i32_e32 vcc, s6, v48
	v_lshl_add_u64 v[48:49], s[8:9], 0, v[52:53]
	v_add_u32_e32 v52, 0xfffff003, v64
	v_mov_b32_e32 v53, v149
	v_lshlrev_b64 v[52:53], 12, v[52:53]
	v_cndmask_b32_e64 v50, v68, 0, vcc
	v_lshl_add_u64 v[52:53], s[10:11], 0, v[52:53]
	v_add_u32_e32 v50, s4, v50
	v_cndmask_b32_e32 v48, v52, v48, vcc
	v_mul_lo_u32 v52, v50, s24
	v_cndmask_b32_e32 v49, v53, v49, vcc
	v_ashrrev_i32_e32 v53, 31, v52
	v_lshl_add_u64 v[52:53], v[52:53], 2, s[82:83]
	v_lshl_add_u64 v[52:53], v[52:53], 0, s[0:1]
	v_lshl_add_u64 v[48:49], v[48:49], 0, s[0:1]
	v_lshl_add_u64 v[52:53], v[52:53], 0, v[148:149]
	v_cndmask_b32_e64 v49, v57, v49, s[36:37]
	v_cndmask_b32_e64 v48, v56, v48, s[36:37]
	v_lshl_add_u64 v[52:53], v[52:53], 0, v[160:161]
	v_lshl_add_u64 v[60:61], v[56:57], 0, v[148:149]
	v_lshl_add_u64 v[56:57], v[52:53], 0, s[14:15]
	v_lshl_add_u64 v[48:49], v[48:49], 0, v[148:149]
	v_add_co_u32_e32 v52, vcc, s12, v52
	v_lshl_add_u64 v[48:49], v[48:49], 0, v[160:161]
	s_nop 0
	v_addc_co_u32_e32 v53, vcc, 0, v53, vcc
	global_load_dword v234, v[48:49], off
	v_lshl_add_u64 v[60:61], v[60:61], 0, v[160:161]
	global_load_dword v238, v[52:53], off
	global_load_dword v235, v[48:49], off offset:64
	global_load_dword v239, v[56:57], off offset:64
	global_load_dword v236, v[48:49], off offset:128
	global_load_dword v240, v[56:57], off offset:128
	global_load_dword v237, v[48:49], off offset:192
	global_load_dword v241, v[56:57], off offset:192
	v_mov_b32_e32 v242, v63
	v_mov_b32_e32 v243, v59
	v_mov_b32_e32 v244, v55
	v_mov_b32_e32 v245, v51
	v_mov_b64_e32 v[220:221], v[60:61]
	s_waitcnt vmcnt(24)
	v_fmac_f32_e32 v112, v120, v116
	v_fmac_f32_e32 v113, v121, v117
	v_fmac_f32_e32 v114, v122, v118
	v_fmac_f32_e32 v115, v123, v119
	global_store_dword v[124:125], v112, off
	global_store_dword v[124:125], v113, off offset:64
	global_store_dword v[124:125], v114, off offset:128
	global_store_dword v[124:125], v115, off offset:192
	v_mov_b32_e32 v59, v149
	v_add_u32_e32 v49, 0xfffff030, v98
	v_add_u32_e32 v48, v98, v169
	v_lshrrev_b32_e32 v49, 12, v49
	v_add_u32_e32 v52, 1, v49
	v_ashrrev_i32_e32 v49, 31, v48
	v_add_u32_e32 v58, 0xfffff000, v48
	v_lshlrev_b64 v[54:55], 12, v[48:49]
	v_lshlrev_b64 v[58:59], 12, v[58:59]
	v_lshl_add_u64 v[56:57], s[2:3], 0, v[54:55]
	v_cmp_gt_i32_e32 vcc, s6, v48
	v_lshl_add_u64 v[54:55], s[8:9], 0, v[54:55]
	v_lshl_add_u64 v[58:59], s[10:11], 0, v[58:59]
	v_cndmask_b32_e32 v55, v59, v55, vcc
	v_cndmask_b32_e32 v54, v58, v54, vcc
	v_cndmask_b32_e64 v49, v52, 0, vcc
	v_lshl_add_u64 v[54:55], v[54:55], 0, s[0:1]
	v_add_u32_e32 v49, s4, v49
	v_lshl_add_u64 v[50:51], v[56:57], 0, v[148:149]
	v_cndmask_b32_e64 v54, v56, v54, s[36:37]
	v_mul_lo_u32 v56, v49, s24
	v_cndmask_b32_e64 v55, v57, v55, s[36:37]
	v_ashrrev_i32_e32 v57, 31, v56
	v_lshl_add_u64 v[56:57], v[56:57], 2, s[82:83]
	v_lshl_add_u64 v[56:57], v[56:57], 0, s[0:1]
	v_lshl_add_u64 v[56:57], v[56:57], 0, v[148:149]
	v_lshl_add_u64 v[56:57], v[56:57], 0, v[160:161]
	v_lshl_add_u64 v[58:59], v[56:57], 0, s[14:15]
	v_lshl_add_u64 v[54:55], v[54:55], 0, v[148:149]
	v_add_co_u32_e32 v56, vcc, s12, v56
	v_lshl_add_u64 v[54:55], v[54:55], 0, v[160:161]
	s_nop 0
	v_addc_co_u32_e32 v57, vcc, 0, v57, vcc
	global_load_dword v112, v[54:55], off
	global_load_dword v116, v[56:57], off
	v_lshl_add_u64 v[50:51], v[50:51], 0, v[160:161]
	global_load_dword v113, v[54:55], off offset:64
	global_load_dword v117, v[58:59], off offset:64
	global_load_dword v114, v[54:55], off offset:128
	global_load_dword v118, v[58:59], off offset:128
	global_load_dword v115, v[54:55], off offset:192
	global_load_dword v119, v[58:59], off offset:192
	v_mov_b32_e32 v120, v44
	v_mov_b32_e32 v121, v40
	v_mov_b32_e32 v122, v36
	v_mov_b32_e32 v123, v32
	v_mov_b64_e32 v[124:125], v[50:51]
	s_waitcnt vmcnt(24)
	v_fmac_f32_e32 v126, v134, v130
	v_fmac_f32_e32 v127, v135, v131
	v_fmac_f32_e32 v128, v136, v132
	v_fmac_f32_e32 v129, v137, v133
	global_store_dword v[138:139], v126, off
	global_store_dword v[138:139], v127, off offset:64
	global_store_dword v[138:139], v128, off offset:128
	global_store_dword v[138:139], v129, off offset:192
	v_or_b32_e32 v50, 1, v48
	v_ashrrev_i32_e32 v51, 31, v50
	v_lshlrev_b64 v[54:55], 12, v[50:51]
	v_lshl_add_u64 v[56:57], s[2:3], 0, v[54:55]
	v_cmp_gt_i32_e32 vcc, s6, v50
	v_lshl_add_u64 v[50:51], s[8:9], 0, v[54:55]
	v_add_u32_e32 v54, 0xfffff001, v48
	v_mov_b32_e32 v55, v149
	v_lshlrev_b64 v[54:55], 12, v[54:55]
	v_cndmask_b32_e64 v32, v52, 0, vcc
	v_lshl_add_u64 v[54:55], s[10:11], 0, v[54:55]
	v_add_u32_e32 v32, s4, v32
	v_cndmask_b32_e32 v50, v54, v50, vcc
	v_mul_lo_u32 v54, v32, s24
	v_cndmask_b32_e32 v51, v55, v51, vcc
	v_ashrrev_i32_e32 v55, 31, v54
	v_lshl_add_u64 v[54:55], v[54:55], 2, s[82:83]
	v_lshl_add_u64 v[54:55], v[54:55], 0, s[0:1]
	v_lshl_add_u64 v[50:51], v[50:51], 0, s[0:1]
	v_lshl_add_u64 v[54:55], v[54:55], 0, v[148:149]
	v_cndmask_b32_e64 v51, v57, v51, s[36:37]
	v_cndmask_b32_e64 v50, v56, v50, s[36:37]
	v_lshl_add_u64 v[54:55], v[54:55], 0, v[160:161]
	v_lshl_add_u64 v[58:59], v[56:57], 0, v[148:149]
	v_lshl_add_u64 v[56:57], v[54:55], 0, s[14:15]
	v_lshl_add_u64 v[50:51], v[50:51], 0, v[148:149]
	v_add_co_u32_e32 v54, vcc, s12, v54
	v_lshl_add_u64 v[50:51], v[50:51], 0, v[160:161]
	s_nop 0
	v_addc_co_u32_e32 v55, vcc, 0, v55, vcc
	global_load_dword v126, v[50:51], off
	global_load_dword v130, v[54:55], off
	v_lshl_add_u64 v[58:59], v[58:59], 0, v[160:161]
	global_load_dword v127, v[50:51], off offset:64
	global_load_dword v131, v[56:57], off offset:64
	global_load_dword v128, v[50:51], off offset:128
	global_load_dword v132, v[56:57], off offset:128
	global_load_dword v129, v[50:51], off offset:192
	global_load_dword v133, v[56:57], off offset:192
	v_mov_b32_e32 v134, v45
	v_mov_b32_e32 v135, v41
	v_mov_b32_e32 v136, v37
	v_mov_b32_e32 v137, v33
	v_mov_b64_e32 v[138:139], v[58:59]
	s_waitcnt vmcnt(24)
	v_fmac_f32_e32 v234, v242, v238
	v_fmac_f32_e32 v235, v243, v239
	v_fmac_f32_e32 v236, v244, v240
	v_fmac_f32_e32 v237, v245, v241
	global_store_dword v[220:221], v234, off
	global_store_dword v[220:221], v235, off offset:64
	global_store_dword v[220:221], v236, off offset:128
	global_store_dword v[220:221], v237, off offset:192
	v_or_b32_e32 v32, 2, v48
	v_ashrrev_i32_e32 v33, 31, v32
	v_lshlrev_b64 v[36:37], 12, v[32:33]
	v_lshl_add_u64 v[40:41], s[2:3], 0, v[36:37]
	v_cmp_gt_i32_e32 vcc, s6, v32
	v_lshl_add_u64 v[32:33], s[8:9], 0, v[36:37]
	v_add_u32_e32 v36, 0xfffff002, v48
	v_mov_b32_e32 v37, v149
	v_lshlrev_b64 v[36:37], 12, v[36:37]
	v_lshl_add_u64 v[36:37], s[10:11], 0, v[36:37]
	v_cndmask_b32_e32 v32, v36, v32, vcc
	v_cndmask_b32_e64 v36, v52, 0, vcc
	v_add_u32_e32 v36, s4, v36
	v_mul_lo_u32 v36, v36, s24
	v_cndmask_b32_e32 v33, v37, v33, vcc
	v_ashrrev_i32_e32 v37, 31, v36
	v_lshl_add_u64 v[36:37], v[36:37], 2, s[82:83]
	v_lshl_add_u64 v[36:37], v[36:37], 0, s[0:1]
	v_lshl_add_u64 v[32:33], v[32:33], 0, s[0:1]
	v_lshl_add_u64 v[36:37], v[36:37], 0, v[148:149]
	v_cndmask_b32_e64 v33, v41, v33, s[36:37]
	v_cndmask_b32_e64 v32, v40, v32, s[36:37]
	v_lshl_add_u64 v[36:37], v[36:37], 0, v[160:161]
	v_lshl_add_u64 v[44:45], v[40:41], 0, v[148:149]
	v_lshl_add_u64 v[40:41], v[36:37], 0, s[14:15]
	v_lshl_add_u64 v[32:33], v[32:33], 0, v[148:149]
	v_add_co_u32_e32 v36, vcc, s12, v36
	v_lshl_add_u64 v[32:33], v[32:33], 0, v[160:161]
	s_nop 0
	v_addc_co_u32_e32 v37, vcc, 0, v37, vcc
	global_load_dword v234, v[32:33], off
	v_lshl_add_u64 v[44:45], v[44:45], 0, v[160:161]
	global_load_dword v238, v[36:37], off
	global_load_dword v235, v[32:33], off offset:64
	global_load_dword v239, v[40:41], off offset:64
	global_load_dword v236, v[32:33], off offset:128
	global_load_dword v240, v[40:41], off offset:128
	global_load_dword v237, v[32:33], off offset:192
	global_load_dword v241, v[40:41], off offset:192
	v_mov_b32_e32 v242, v46
	v_mov_b32_e32 v243, v42
	v_mov_b32_e32 v244, v38
	v_mov_b32_e32 v245, v34
	v_mov_b64_e32 v[220:221], v[44:45]
	s_waitcnt vmcnt(24)
	v_fmac_f32_e32 v112, v120, v116
	v_fmac_f32_e32 v113, v121, v117
	v_fmac_f32_e32 v114, v122, v118
	v_fmac_f32_e32 v115, v123, v119
	global_store_dword v[124:125], v112, off
	global_store_dword v[124:125], v113, off offset:64
	global_store_dword v[124:125], v114, off offset:128
	global_store_dword v[124:125], v115, off offset:192
	v_or_b32_e32 v32, 3, v48
	v_ashrrev_i32_e32 v33, 31, v32
	v_lshlrev_b64 v[36:37], 12, v[32:33]
	v_lshl_add_u64 v[40:41], s[2:3], 0, v[36:37]
	v_cmp_gt_i32_e32 vcc, s6, v32
	v_lshl_add_u64 v[32:33], s[8:9], 0, v[36:37]
	v_add_u32_e32 v36, 0xfffff003, v48
	v_mov_b32_e32 v37, v149
	v_lshlrev_b64 v[36:37], 12, v[36:37]
	v_cndmask_b32_e64 v34, v52, 0, vcc
	v_lshl_add_u64 v[36:37], s[10:11], 0, v[36:37]
	v_add_u32_e32 v34, s4, v34
	v_cndmask_b32_e32 v32, v36, v32, vcc
	v_mul_lo_u32 v36, v34, s24
	v_cndmask_b32_e32 v33, v37, v33, vcc
	v_ashrrev_i32_e32 v37, 31, v36
	v_lshl_add_u64 v[36:37], v[36:37], 2, s[82:83]
	v_lshl_add_u64 v[36:37], v[36:37], 0, s[0:1]
	v_lshl_add_u64 v[32:33], v[32:33], 0, s[0:1]
	v_lshl_add_u64 v[36:37], v[36:37], 0, v[148:149]
	v_cndmask_b32_e64 v33, v41, v33, s[36:37]
	v_cndmask_b32_e64 v32, v40, v32, s[36:37]
	v_lshl_add_u64 v[36:37], v[36:37], 0, v[160:161]
	v_lshl_add_u64 v[44:45], v[40:41], 0, v[148:149]
	v_lshl_add_u64 v[40:41], v[36:37], 0, s[14:15]
	v_lshl_add_u64 v[32:33], v[32:33], 0, v[148:149]
	v_add_co_u32_e32 v36, vcc, s12, v36
	v_lshl_add_u64 v[32:33], v[32:33], 0, v[160:161]
	s_nop 0
	v_addc_co_u32_e32 v37, vcc, 0, v37, vcc
	global_load_dword v112, v[32:33], off
	v_lshl_add_u64 v[44:45], v[44:45], 0, v[160:161]
	global_load_dword v116, v[36:37], off
	global_load_dword v113, v[32:33], off offset:64
	global_load_dword v117, v[40:41], off offset:64
	global_load_dword v114, v[32:33], off offset:128
	global_load_dword v118, v[40:41], off offset:128
	global_load_dword v115, v[32:33], off offset:192
	global_load_dword v119, v[40:41], off offset:192
	v_mov_b32_e32 v120, v47
	v_mov_b32_e32 v121, v43
	v_mov_b32_e32 v122, v39
	v_mov_b32_e32 v123, v35
	v_mov_b64_e32 v[124:125], v[44:45]
	s_waitcnt vmcnt(24)
	v_fmac_f32_e32 v126, v134, v130
	v_fmac_f32_e32 v127, v135, v131
	v_fmac_f32_e32 v128, v136, v132
	v_fmac_f32_e32 v129, v137, v133
	global_store_dword v[138:139], v126, off
	global_store_dword v[138:139], v127, off offset:64
	global_store_dword v[138:139], v128, off offset:128
	global_store_dword v[138:139], v129, off offset:192
	v_mov_b32_e32 v43, v149
	v_add_u32_e32 v33, 0xfffff040, v98
	v_add_u32_e32 v32, v98, v170
	v_lshrrev_b32_e32 v33, 12, v33
	v_add_u32_e32 v36, 1, v33
	v_ashrrev_i32_e32 v33, 31, v32
	v_add_u32_e32 v42, 0xfffff000, v32
	v_lshlrev_b64 v[38:39], 12, v[32:33]
	v_lshlrev_b64 v[42:43], 12, v[42:43]
	v_lshl_add_u64 v[40:41], s[2:3], 0, v[38:39]
	v_cmp_gt_i32_e32 vcc, s6, v32
	v_lshl_add_u64 v[38:39], s[8:9], 0, v[38:39]
	v_lshl_add_u64 v[42:43], s[10:11], 0, v[42:43]
	v_cndmask_b32_e32 v39, v43, v39, vcc
	v_cndmask_b32_e32 v38, v42, v38, vcc
	v_cndmask_b32_e64 v33, v36, 0, vcc
	v_lshl_add_u64 v[38:39], v[38:39], 0, s[0:1]
	v_add_u32_e32 v33, s4, v33
	v_lshl_add_u64 v[34:35], v[40:41], 0, v[148:149]
	v_cndmask_b32_e64 v38, v40, v38, s[36:37]
	v_mul_lo_u32 v40, v33, s24
	v_cndmask_b32_e64 v39, v41, v39, s[36:37]
	v_ashrrev_i32_e32 v41, 31, v40
	v_lshl_add_u64 v[40:41], v[40:41], 2, s[82:83]
	v_lshl_add_u64 v[40:41], v[40:41], 0, s[0:1]
	v_lshl_add_u64 v[40:41], v[40:41], 0, v[148:149]
	v_lshl_add_u64 v[40:41], v[40:41], 0, v[160:161]
	v_lshl_add_u64 v[42:43], v[40:41], 0, s[14:15]
	v_lshl_add_u64 v[38:39], v[38:39], 0, v[148:149]
	v_add_co_u32_e32 v40, vcc, s12, v40
	v_lshl_add_u64 v[38:39], v[38:39], 0, v[160:161]
	s_nop 0
	v_addc_co_u32_e32 v41, vcc, 0, v41, vcc
	global_load_dword v126, v[38:39], off
	global_load_dword v130, v[40:41], off
	v_lshl_add_u64 v[34:35], v[34:35], 0, v[160:161]
	global_load_dword v127, v[38:39], off offset:64
	global_load_dword v131, v[42:43], off offset:64
	global_load_dword v128, v[38:39], off offset:128
	global_load_dword v132, v[42:43], off offset:128
	global_load_dword v129, v[38:39], off offset:192
	global_load_dword v133, v[42:43], off offset:192
	v_mov_b32_e32 v134, v28
	v_mov_b32_e32 v135, v24
	v_mov_b32_e32 v136, v20
	v_mov_b32_e32 v137, v16
	v_mov_b64_e32 v[138:139], v[34:35]
	s_waitcnt vmcnt(24)
	v_fmac_f32_e32 v234, v242, v238
	v_fmac_f32_e32 v235, v243, v239
	v_fmac_f32_e32 v236, v244, v240
	v_fmac_f32_e32 v237, v245, v241
	global_store_dword v[220:221], v234, off
	global_store_dword v[220:221], v235, off offset:64
	global_store_dword v[220:221], v236, off offset:128
	global_store_dword v[220:221], v237, off offset:192
	v_or_b32_e32 v34, 1, v32
	v_ashrrev_i32_e32 v35, 31, v34
	v_lshlrev_b64 v[38:39], 12, v[34:35]
	v_lshl_add_u64 v[40:41], s[2:3], 0, v[38:39]
	v_cmp_gt_i32_e32 vcc, s6, v34
	v_lshl_add_u64 v[34:35], s[8:9], 0, v[38:39]
	v_add_u32_e32 v38, 0xfffff001, v32
	v_mov_b32_e32 v39, v149
	v_lshlrev_b64 v[38:39], 12, v[38:39]
	v_cndmask_b32_e64 v16, v36, 0, vcc
	v_lshl_add_u64 v[38:39], s[10:11], 0, v[38:39]
	v_add_u32_e32 v16, s4, v16
	v_cndmask_b32_e32 v34, v38, v34, vcc
	v_mul_lo_u32 v38, v16, s24
	v_cndmask_b32_e32 v35, v39, v35, vcc
	v_ashrrev_i32_e32 v39, 31, v38
	v_lshl_add_u64 v[38:39], v[38:39], 2, s[82:83]
	v_lshl_add_u64 v[38:39], v[38:39], 0, s[0:1]
	v_lshl_add_u64 v[34:35], v[34:35], 0, s[0:1]
	v_lshl_add_u64 v[38:39], v[38:39], 0, v[148:149]
	v_cndmask_b32_e64 v35, v41, v35, s[36:37]
	v_cndmask_b32_e64 v34, v40, v34, s[36:37]
	v_lshl_add_u64 v[38:39], v[38:39], 0, v[160:161]
	v_lshl_add_u64 v[42:43], v[40:41], 0, v[148:149]
	v_lshl_add_u64 v[40:41], v[38:39], 0, s[14:15]
	v_lshl_add_u64 v[34:35], v[34:35], 0, v[148:149]
	v_add_co_u32_e32 v38, vcc, s12, v38
	v_lshl_add_u64 v[34:35], v[34:35], 0, v[160:161]
	s_nop 0
	v_addc_co_u32_e32 v39, vcc, 0, v39, vcc
	global_load_dword v234, v[34:35], off
	global_load_dword v238, v[38:39], off
	v_lshl_add_u64 v[42:43], v[42:43], 0, v[160:161]
	global_load_dword v235, v[34:35], off offset:64
	global_load_dword v239, v[40:41], off offset:64
	global_load_dword v236, v[34:35], off offset:128
	global_load_dword v240, v[40:41], off offset:128
	global_load_dword v237, v[34:35], off offset:192
	global_load_dword v241, v[40:41], off offset:192
	v_mov_b32_e32 v242, v29
	v_mov_b32_e32 v243, v25
	v_mov_b32_e32 v244, v21
	v_mov_b32_e32 v245, v17
	v_mov_b64_e32 v[220:221], v[42:43]
	s_waitcnt vmcnt(24)
	v_fmac_f32_e32 v112, v120, v116
	v_fmac_f32_e32 v113, v121, v117
	v_fmac_f32_e32 v114, v122, v118
	v_fmac_f32_e32 v115, v123, v119
	global_store_dword v[124:125], v112, off
	global_store_dword v[124:125], v113, off offset:64
	global_store_dword v[124:125], v114, off offset:128
	global_store_dword v[124:125], v115, off offset:192
	v_or_b32_e32 v16, 2, v32
	v_ashrrev_i32_e32 v17, 31, v16
	v_lshlrev_b64 v[20:21], 12, v[16:17]
	v_lshl_add_u64 v[24:25], s[2:3], 0, v[20:21]
	v_cmp_gt_i32_e32 vcc, s6, v16
	v_lshl_add_u64 v[16:17], s[8:9], 0, v[20:21]
	v_add_u32_e32 v20, 0xfffff002, v32
	v_mov_b32_e32 v21, v149
	v_lshlrev_b64 v[20:21], 12, v[20:21]
	v_lshl_add_u64 v[20:21], s[10:11], 0, v[20:21]
	v_cndmask_b32_e32 v16, v20, v16, vcc
	v_cndmask_b32_e64 v20, v36, 0, vcc
	v_add_u32_e32 v20, s4, v20
	v_mul_lo_u32 v20, v20, s24
	v_cndmask_b32_e32 v17, v21, v17, vcc
	v_ashrrev_i32_e32 v21, 31, v20
	v_lshl_add_u64 v[20:21], v[20:21], 2, s[82:83]
	v_lshl_add_u64 v[20:21], v[20:21], 0, s[0:1]
	v_lshl_add_u64 v[16:17], v[16:17], 0, s[0:1]
	v_lshl_add_u64 v[20:21], v[20:21], 0, v[148:149]
	v_cndmask_b32_e64 v17, v25, v17, s[36:37]
	v_cndmask_b32_e64 v16, v24, v16, s[36:37]
	v_lshl_add_u64 v[20:21], v[20:21], 0, v[160:161]
	v_lshl_add_u64 v[28:29], v[24:25], 0, v[148:149]
	v_lshl_add_u64 v[24:25], v[20:21], 0, s[14:15]
	v_lshl_add_u64 v[16:17], v[16:17], 0, v[148:149]
	v_add_co_u32_e32 v20, vcc, s12, v20
	v_lshl_add_u64 v[16:17], v[16:17], 0, v[160:161]
	s_nop 0
	v_addc_co_u32_e32 v21, vcc, 0, v21, vcc
	global_load_dword v112, v[16:17], off
	v_lshl_add_u64 v[28:29], v[28:29], 0, v[160:161]
	global_load_dword v116, v[20:21], off
	global_load_dword v113, v[16:17], off offset:64
	global_load_dword v117, v[24:25], off offset:64
	global_load_dword v114, v[16:17], off offset:128
	global_load_dword v118, v[24:25], off offset:128
	global_load_dword v115, v[16:17], off offset:192
	global_load_dword v119, v[24:25], off offset:192
	v_mov_b32_e32 v120, v30
	v_mov_b32_e32 v121, v26
	v_mov_b32_e32 v122, v22
	v_mov_b32_e32 v123, v18
	v_mov_b64_e32 v[124:125], v[28:29]
	s_waitcnt vmcnt(24)
	v_fmac_f32_e32 v126, v134, v130
	v_fmac_f32_e32 v127, v135, v131
	v_fmac_f32_e32 v128, v136, v132
	v_fmac_f32_e32 v129, v137, v133
	global_store_dword v[138:139], v126, off
	global_store_dword v[138:139], v127, off offset:64
	global_store_dword v[138:139], v128, off offset:128
	global_store_dword v[138:139], v129, off offset:192
	v_or_b32_e32 v16, 3, v32
	v_ashrrev_i32_e32 v17, 31, v16
	v_lshlrev_b64 v[20:21], 12, v[16:17]
	v_lshl_add_u64 v[24:25], s[2:3], 0, v[20:21]
	v_cmp_gt_i32_e32 vcc, s6, v16
	v_lshl_add_u64 v[16:17], s[8:9], 0, v[20:21]
	v_add_u32_e32 v20, 0xfffff003, v32
	v_mov_b32_e32 v21, v149
	v_lshlrev_b64 v[20:21], 12, v[20:21]
	v_cndmask_b32_e64 v18, v36, 0, vcc
	v_lshl_add_u64 v[20:21], s[10:11], 0, v[20:21]
	v_add_u32_e32 v18, s4, v18
	v_cndmask_b32_e32 v16, v20, v16, vcc
	v_mul_lo_u32 v20, v18, s24
	v_cndmask_b32_e32 v17, v21, v17, vcc
	v_ashrrev_i32_e32 v21, 31, v20
	v_lshl_add_u64 v[20:21], v[20:21], 2, s[82:83]
	v_lshl_add_u64 v[20:21], v[20:21], 0, s[0:1]
	v_lshl_add_u64 v[16:17], v[16:17], 0, s[0:1]
	v_lshl_add_u64 v[20:21], v[20:21], 0, v[148:149]
	v_cndmask_b32_e64 v17, v25, v17, s[36:37]
	v_cndmask_b32_e64 v16, v24, v16, s[36:37]
	v_lshl_add_u64 v[20:21], v[20:21], 0, v[160:161]
	v_lshl_add_u64 v[28:29], v[24:25], 0, v[148:149]
	v_lshl_add_u64 v[24:25], v[20:21], 0, s[14:15]
	v_lshl_add_u64 v[16:17], v[16:17], 0, v[148:149]
	v_add_co_u32_e32 v20, vcc, s12, v20
	v_lshl_add_u64 v[16:17], v[16:17], 0, v[160:161]
	s_nop 0
	v_addc_co_u32_e32 v21, vcc, 0, v21, vcc
	global_load_dword v126, v[16:17], off
	v_lshl_add_u64 v[28:29], v[28:29], 0, v[160:161]
	global_load_dword v130, v[20:21], off
	global_load_dword v127, v[16:17], off offset:64
	global_load_dword v131, v[24:25], off offset:64
	global_load_dword v128, v[16:17], off offset:128
	global_load_dword v132, v[24:25], off offset:128
	global_load_dword v129, v[16:17], off offset:192
	global_load_dword v133, v[24:25], off offset:192
	v_mov_b32_e32 v134, v31
	v_mov_b32_e32 v135, v27
	v_mov_b32_e32 v136, v23
	v_mov_b32_e32 v137, v19
	v_mov_b64_e32 v[138:139], v[28:29]
	s_waitcnt vmcnt(24)
	v_fmac_f32_e32 v234, v242, v238
	v_fmac_f32_e32 v235, v243, v239
	v_fmac_f32_e32 v236, v244, v240
	v_fmac_f32_e32 v237, v245, v241
	global_store_dword v[220:221], v234, off
	global_store_dword v[220:221], v235, off offset:64
	global_store_dword v[220:221], v236, off offset:128
	global_store_dword v[220:221], v237, off offset:192
	v_mov_b32_e32 v27, v149
	v_add_u32_e32 v17, 0xfffff050, v98
	v_add_u32_e32 v16, v98, v171
	v_lshrrev_b32_e32 v17, 12, v17
	v_add_u32_e32 v20, 1, v17
	v_ashrrev_i32_e32 v17, 31, v16
	v_add_u32_e32 v26, 0xfffff000, v16
	v_lshlrev_b64 v[22:23], 12, v[16:17]
	v_lshlrev_b64 v[26:27], 12, v[26:27]
	v_lshl_add_u64 v[24:25], s[2:3], 0, v[22:23]
	v_cmp_gt_i32_e32 vcc, s6, v16
	v_lshl_add_u64 v[22:23], s[8:9], 0, v[22:23]
	v_lshl_add_u64 v[26:27], s[10:11], 0, v[26:27]
	v_cndmask_b32_e32 v23, v27, v23, vcc
	v_cndmask_b32_e32 v22, v26, v22, vcc
	v_cndmask_b32_e64 v17, v20, 0, vcc
	v_lshl_add_u64 v[22:23], v[22:23], 0, s[0:1]
	v_add_u32_e32 v17, s4, v17
	v_lshl_add_u64 v[18:19], v[24:25], 0, v[148:149]
	v_cndmask_b32_e64 v22, v24, v22, s[36:37]
	v_mul_lo_u32 v24, v17, s24
	v_cndmask_b32_e64 v23, v25, v23, s[36:37]
	v_ashrrev_i32_e32 v25, 31, v24
	v_lshl_add_u64 v[24:25], v[24:25], 2, s[82:83]
	v_lshl_add_u64 v[24:25], v[24:25], 0, s[0:1]
	v_lshl_add_u64 v[24:25], v[24:25], 0, v[148:149]
	v_lshl_add_u64 v[24:25], v[24:25], 0, v[160:161]
	v_lshl_add_u64 v[26:27], v[24:25], 0, s[14:15]
	v_lshl_add_u64 v[22:23], v[22:23], 0, v[148:149]
	v_add_co_u32_e32 v24, vcc, s12, v24
	v_lshl_add_u64 v[22:23], v[22:23], 0, v[160:161]
	s_nop 0
	v_addc_co_u32_e32 v25, vcc, 0, v25, vcc
	global_load_dword v234, v[22:23], off
	global_load_dword v238, v[24:25], off
	v_lshl_add_u64 v[18:19], v[18:19], 0, v[160:161]
	global_load_dword v235, v[22:23], off offset:64
	global_load_dword v239, v[26:27], off offset:64
	global_load_dword v236, v[22:23], off offset:128
	global_load_dword v240, v[26:27], off offset:128
	global_load_dword v237, v[22:23], off offset:192
	global_load_dword v241, v[26:27], off offset:192
	v_mov_b32_e32 v242, v12
	v_mov_b32_e32 v243, v8
	v_mov_b32_e32 v244, v4
	v_mov_b32_e32 v245, v0
	v_mov_b64_e32 v[220:221], v[18:19]
	s_waitcnt vmcnt(24)
	v_fmac_f32_e32 v112, v120, v116
	v_fmac_f32_e32 v113, v121, v117
	v_fmac_f32_e32 v114, v122, v118
	v_fmac_f32_e32 v115, v123, v119
	global_store_dword v[124:125], v112, off
	global_store_dword v[124:125], v113, off offset:64
	global_store_dword v[124:125], v114, off offset:128
	global_store_dword v[124:125], v115, off offset:192
	v_or_b32_e32 v18, 1, v16
	v_ashrrev_i32_e32 v19, 31, v18
	v_lshlrev_b64 v[22:23], 12, v[18:19]
	v_lshl_add_u64 v[24:25], s[2:3], 0, v[22:23]
	v_cmp_gt_i32_e32 vcc, s6, v18
	v_lshl_add_u64 v[18:19], s[8:9], 0, v[22:23]
	v_add_u32_e32 v22, 0xfffff001, v16
	v_mov_b32_e32 v23, v149
	v_lshlrev_b64 v[22:23], 12, v[22:23]
	v_cndmask_b32_e64 v0, v20, 0, vcc
	v_lshl_add_u64 v[22:23], s[10:11], 0, v[22:23]
	v_add_u32_e32 v0, s4, v0
	v_cndmask_b32_e32 v18, v22, v18, vcc
	v_mul_lo_u32 v22, v0, s24
	v_cndmask_b32_e32 v19, v23, v19, vcc
	v_ashrrev_i32_e32 v23, 31, v22
	v_lshl_add_u64 v[22:23], v[22:23], 2, s[82:83]
	v_lshl_add_u64 v[22:23], v[22:23], 0, s[0:1]
	v_lshl_add_u64 v[18:19], v[18:19], 0, s[0:1]
	v_lshl_add_u64 v[22:23], v[22:23], 0, v[148:149]
	v_cndmask_b32_e64 v19, v25, v19, s[36:37]
	v_cndmask_b32_e64 v18, v24, v18, s[36:37]
	v_lshl_add_u64 v[22:23], v[22:23], 0, v[160:161]
	v_lshl_add_u64 v[26:27], v[24:25], 0, v[148:149]
	v_lshl_add_u64 v[24:25], v[22:23], 0, s[14:15]
	v_lshl_add_u64 v[18:19], v[18:19], 0, v[148:149]
	v_add_co_u32_e32 v22, vcc, s12, v22
	v_lshl_add_u64 v[18:19], v[18:19], 0, v[160:161]
	s_nop 0
	v_addc_co_u32_e32 v23, vcc, 0, v23, vcc
	global_load_dword v112, v[18:19], off
	global_load_dword v116, v[22:23], off
	v_lshl_add_u64 v[26:27], v[26:27], 0, v[160:161]
	global_load_dword v113, v[18:19], off offset:64
	global_load_dword v117, v[24:25], off offset:64
	global_load_dword v114, v[18:19], off offset:128
	global_load_dword v118, v[24:25], off offset:128
	global_load_dword v115, v[18:19], off offset:192
	global_load_dword v119, v[24:25], off offset:192
	v_mov_b32_e32 v120, v13
	v_mov_b32_e32 v121, v9
	v_mov_b32_e32 v122, v5
	v_mov_b32_e32 v123, v1
	v_mov_b64_e32 v[124:125], v[26:27]
	s_waitcnt vmcnt(24)
	v_fmac_f32_e32 v126, v134, v130
	v_fmac_f32_e32 v127, v135, v131
	v_fmac_f32_e32 v128, v136, v132
	v_fmac_f32_e32 v129, v137, v133
	global_store_dword v[138:139], v126, off
	global_store_dword v[138:139], v127, off offset:64
	global_store_dword v[138:139], v128, off offset:128
	global_store_dword v[138:139], v129, off offset:192
	v_or_b32_e32 v0, 2, v16
	v_ashrrev_i32_e32 v1, 31, v0
	v_lshlrev_b64 v[4:5], 12, v[0:1]
	v_lshl_add_u64 v[8:9], s[2:3], 0, v[4:5]
	v_cmp_gt_i32_e32 vcc, s6, v0
	v_lshl_add_u64 v[0:1], s[8:9], 0, v[4:5]
	v_add_u32_e32 v4, 0xfffff002, v16
	v_mov_b32_e32 v5, v149
	v_lshlrev_b64 v[4:5], 12, v[4:5]
	v_lshl_add_u64 v[4:5], s[10:11], 0, v[4:5]
	v_cndmask_b32_e32 v0, v4, v0, vcc
	v_cndmask_b32_e64 v4, v20, 0, vcc
	v_add_u32_e32 v4, s4, v4
	v_mul_lo_u32 v4, v4, s24
	v_cndmask_b32_e32 v1, v5, v1, vcc
	v_ashrrev_i32_e32 v5, 31, v4
	v_lshl_add_u64 v[4:5], v[4:5], 2, s[82:83]
	v_lshl_add_u64 v[4:5], v[4:5], 0, s[0:1]
	v_lshl_add_u64 v[0:1], v[0:1], 0, s[0:1]
	v_lshl_add_u64 v[4:5], v[4:5], 0, v[148:149]
	v_cndmask_b32_e64 v1, v9, v1, s[36:37]
	v_cndmask_b32_e64 v0, v8, v0, s[36:37]
	v_lshl_add_u64 v[4:5], v[4:5], 0, v[160:161]
	v_lshl_add_u64 v[12:13], v[8:9], 0, v[148:149]
	v_lshl_add_u64 v[8:9], v[4:5], 0, s[14:15]
	v_lshl_add_u64 v[0:1], v[0:1], 0, v[148:149]
	v_add_co_u32_e32 v4, vcc, s12, v4
	v_lshl_add_u64 v[0:1], v[0:1], 0, v[160:161]
	s_nop 0
	v_addc_co_u32_e32 v5, vcc, 0, v5, vcc
	global_load_dword v126, v[0:1], off
	v_lshl_add_u64 v[12:13], v[12:13], 0, v[160:161]
	global_load_dword v130, v[4:5], off
	global_load_dword v127, v[0:1], off offset:64
	global_load_dword v131, v[8:9], off offset:64
	global_load_dword v128, v[0:1], off offset:128
	global_load_dword v132, v[8:9], off offset:128
	global_load_dword v129, v[0:1], off offset:192
	global_load_dword v133, v[8:9], off offset:192
	v_mov_b32_e32 v134, v14
	v_mov_b32_e32 v135, v10
	v_mov_b32_e32 v136, v6
	v_mov_b32_e32 v137, v2
	v_mov_b64_e32 v[138:139], v[12:13]
	s_waitcnt vmcnt(24)
	v_fmac_f32_e32 v234, v242, v238
	v_fmac_f32_e32 v235, v243, v239
	v_fmac_f32_e32 v236, v244, v240
	v_fmac_f32_e32 v237, v245, v241
	global_store_dword v[220:221], v234, off
	global_store_dword v[220:221], v235, off offset:64
	global_store_dword v[220:221], v236, off offset:128
	global_store_dword v[220:221], v237, off offset:192
	v_or_b32_e32 v0, 3, v16
	v_ashrrev_i32_e32 v1, 31, v0
	v_lshlrev_b64 v[4:5], 12, v[0:1]
	v_lshl_add_u64 v[8:9], s[2:3], 0, v[4:5]
	v_cmp_gt_i32_e32 vcc, s6, v0
	v_lshl_add_u64 v[0:1], s[8:9], 0, v[4:5]
	v_add_u32_e32 v4, 0xfffff003, v16
	v_mov_b32_e32 v5, v149
	v_lshlrev_b64 v[4:5], 12, v[4:5]
	v_cndmask_b32_e64 v2, v20, 0, vcc
	v_lshl_add_u64 v[4:5], s[10:11], 0, v[4:5]
	v_add_u32_e32 v2, s4, v2
	v_cndmask_b32_e32 v0, v4, v0, vcc
	v_mul_lo_u32 v4, v2, s24
	v_cndmask_b32_e32 v1, v5, v1, vcc
	v_ashrrev_i32_e32 v5, 31, v4
	v_lshl_add_u64 v[4:5], v[4:5], 2, s[82:83]
	v_lshl_add_u64 v[4:5], v[4:5], 0, s[0:1]
	v_lshl_add_u64 v[0:1], v[0:1], 0, s[0:1]
	v_lshl_add_u64 v[4:5], v[4:5], 0, v[148:149]
	v_cndmask_b32_e64 v1, v9, v1, s[36:37]
	v_cndmask_b32_e64 v0, v8, v0, s[36:37]
	v_lshl_add_u64 v[4:5], v[4:5], 0, v[160:161]
	v_lshl_add_u64 v[12:13], v[8:9], 0, v[148:149]
	v_lshl_add_u64 v[8:9], v[4:5], 0, s[14:15]
	v_lshl_add_u64 v[0:1], v[0:1], 0, v[148:149]
	v_add_co_u32_e32 v4, vcc, s12, v4
	v_lshl_add_u64 v[0:1], v[0:1], 0, v[160:161]
	s_nop 0
	v_addc_co_u32_e32 v5, vcc, 0, v5, vcc
	global_load_dword v234, v[0:1], off
	v_lshl_add_u64 v[12:13], v[12:13], 0, v[160:161]
	global_load_dword v238, v[4:5], off
	global_load_dword v235, v[0:1], off offset:64
	global_load_dword v239, v[8:9], off offset:64
	global_load_dword v236, v[0:1], off offset:128
	global_load_dword v240, v[8:9], off offset:128
	global_load_dword v237, v[0:1], off offset:192
	global_load_dword v241, v[8:9], off offset:192
	v_mov_b32_e32 v242, v15
	v_mov_b32_e32 v243, v11
	v_mov_b32_e32 v244, v7
	v_mov_b32_e32 v245, v3
	v_mov_b64_e32 v[220:221], v[12:13]
	s_waitcnt vmcnt(24)
	v_fmac_f32_e32 v112, v120, v116
	v_fmac_f32_e32 v113, v121, v117
	v_fmac_f32_e32 v114, v122, v118
	v_fmac_f32_e32 v115, v123, v119
	global_store_dword v[124:125], v112, off
	global_store_dword v[124:125], v113, off offset:64
	global_store_dword v[124:125], v114, off offset:128
	global_store_dword v[124:125], v115, off offset:192
	s_waitcnt vmcnt(16)
	v_fmac_f32_e32 v126, v134, v130
	v_fmac_f32_e32 v127, v135, v131
	v_fmac_f32_e32 v128, v136, v132
	v_fmac_f32_e32 v129, v137, v133
	global_store_dword v[138:139], v126, off
	global_store_dword v[138:139], v127, off offset:64
	global_store_dword v[138:139], v128, off offset:128
	global_store_dword v[138:139], v129, off offset:192
	s_waitcnt vmcnt(8)
	v_fmac_f32_e32 v234, v242, v238
	v_fmac_f32_e32 v235, v243, v239
	v_fmac_f32_e32 v236, v244, v240
	v_fmac_f32_e32 v237, v245, v241
	global_store_dword v[220:221], v234, off
	global_store_dword v[220:221], v235, off offset:64
	global_store_dword v[220:221], v236, off offset:128
	global_store_dword v[220:221], v237, off offset:192
	s_cbranch_scc0 .LBB0_1136
